# gla_prep: batch the 6 serialized tile loads + w2c loads, counted vmcnt; EpiRes hoist with vmcnt(15)
# speedup vs baseline: 1.0137x; 1.0137x over previous
.LBB0_331:
	s_ashr_i32 s35, s34, 11
	s_cmpk_lt_u32 s34, 0x800
	s_cselect_b64 vcc, -1, 0
	s_and_b32 s38, s14, 0x7c0
	s_xor_b32 s39, s38, 0x7ff
	v_sub_u32_e32 v0, s39, v46
	v_add_u32_e32 v1, s38, v46
	s_and_b32 s36, s14, 0x7800
	v_cndmask_b32_e32 v0, v0, v1, vcc
	s_lshl_b32 s12, s35, 4
	v_add_u32_e32 v0, s36, v0
	s_ashr_i32 s13, s12, 31
	v_ashrrev_i32_e32 v1, 31, v0
	v_lshl_add_u64 v[22:23], s[12:13], 2, v[4:5]
	v_lshlrev_b64 v[2:3], 7, v[0:1]
	s_waitcnt lgkmcnt(0)
	s_barrier
	v_lshl_add_u64 v[2:3], v[22:23], 0, v[2:3]
	global_load_dword v80, v[2:3], off
	s_and_b32 s37, s15, 0x180
	s_lshl_b32 s46, s37, 1
	v_lshl_add_u64 v[24:25], v[6:7], 0, s[46:47]
	v_lshlrev_b64 v[0:1], 11, v[0:1]
	v_lshl_add_u64 v[26:27], v[24:25], 0, v[0:1]
	s_lshl_b32 s40, s35, 13
	s_or_b32 s40, s40, s37
	s_movk_i32 s12, 0x1000
	s_lshl_b32 s35, s35, 9
	s_or_b32 s35, s35, s37
	s_mov_b32 s37, 0x7f800000
	s_cmpk_gt_u32 s34, 0x7ff
	global_load_dwordx4 v[64:67], v[26:27], off
	global_load_dwordx4 v[68:71], v[26:27], off offset:1024
	v_sub_u32_e32 v0, s39, v47
	v_add_u32_e32 v1, s38, v47
	v_cndmask_b32_e32 v0, v0, v1, vcc
	v_add_u32_e32 v0, s36, v0
	v_ashrrev_i32_e32 v1, 31, v0
	v_lshlrev_b64 v[2:3], 7, v[0:1]
	v_lshl_add_u64 v[2:3], v[22:23], 0, v[2:3]
	global_load_dword v81, v[2:3], off
	v_lshlrev_b64 v[0:1], 11, v[0:1]
	v_lshl_add_u64 v[22:23], v[24:25], 0, v[0:1]
	s_mov_b32 s36, 0x3f317217
	global_load_dwordx4 v[72:75], v[22:23], off
	global_load_dwordx4 v[76:79], v[22:23], off offset:1024
	v_or_b32_e32 v0, s40, v42
	v_ashrrev_i32_e32 v1, 31, v0
	v_lshl_add_u64 v[2:3], v[0:1], 2, s[28:29]
	v_add_co_u32_e32 v0, vcc, s12, v2
	s_movk_i32 s12, 0x2000
	s_nop 0
	v_addc_co_u32_e32 v1, vcc, 0, v3, vcc
	v_add_co_u32_e32 v22, vcc, s12, v2
	s_movk_i32 s12, 0x3000
	s_nop 0
	v_addc_co_u32_e32 v23, vcc, 0, v3, vcc
	global_load_dword v30, v[2:3], off
	global_load_dword v31, v[2:3], off offset:2048
	global_load_dword v32, v[22:23], off offset:-4096
	global_load_dword v33, v[0:1], off offset:2048
	global_load_dword v26, v[22:23], off
	global_load_dword v27, v[22:23], off offset:2048
	v_add_co_u32_e32 v0, vcc, s12, v2
	s_movk_i32 s12, 0x4000
	s_nop 0
	v_addc_co_u32_e32 v1, vcc, 0, v3, vcc
	v_add_co_u32_e32 v24, vcc, s12, v2
	s_movk_i32 s12, 0x5000
	s_nop 0
	v_addc_co_u32_e32 v25, vcc, 0, v3, vcc
	global_load_dword v28, v[24:25], off offset:-4096
	global_load_dword v29, v[0:1], off offset:2048
	global_load_dword v22, v[24:25], off
	global_load_dword v23, v[24:25], off offset:2048
	v_add_co_u32_e32 v0, vcc, s12, v2
	s_movk_i32 s12, 0x6000
	s_nop 0
	v_addc_co_u32_e32 v1, vcc, 0, v3, vcc
	v_add_co_u32_e32 v34, vcc, s12, v2
	s_movk_i32 s12, 0x7000
	s_nop 0
	v_addc_co_u32_e32 v35, vcc, 0, v3, vcc
	global_load_dword v24, v[34:35], off offset:-4096
	global_load_dword v25, v[0:1], off offset:2048
	s_nop 0
	global_load_dword v0, v[34:35], off
	global_load_dword v1, v[34:35], off offset:2048
	v_add_co_u32_e32 v34, vcc, s12, v2
	s_nop 1
	v_addc_co_u32_e32 v35, vcc, 0, v3, vcc
	global_load_dword v2, v[34:35], off
	global_load_dword v3, v[34:35], off offset:2048
	v_or_b32_e32 v34, s35, v42
	v_ashrrev_i32_e32 v35, 31, v34
	v_lshl_add_u64 v[34:35], v[34:35], 2, s[30:31]
	global_load_dword v35, v[34:35], off
	s_waitcnt vmcnt(22)
	ds_write_b32 v44, v80
	s_waitcnt vmcnt(21)
	ds_write_b128 v11, v[64:67] offset:8192
	s_waitcnt vmcnt(20)
	ds_write_b128 v11, v[68:71] offset:25600
	s_waitcnt vmcnt(19)
	ds_write_b32 v44, v81 offset:2048
	s_waitcnt vmcnt(18)
	ds_write_b128 v48, v[72:75] offset:8192
	s_waitcnt vmcnt(17)
	ds_write_b128 v48, v[76:79] offset:25600
	s_waitcnt lgkmcnt(0)
	s_barrier
	ds_read_b128 v[36:39], v43
	ds_read_b128 v[50:53], v43 offset:16
	ds_read_b128 v[54:57], v43 offset:32
	ds_read_b128 v[58:61], v43 offset:48
	s_mov_b32 s35, 0xbfb8aa3b
	s_waitcnt vmcnt(0) lgkmcnt(3)
	v_fma_f32 v34, v30, v36, v35
	v_fmac_f32_e32 v34, v31, v37
	v_fmac_f32_e32 v34, v32, v38
	v_fmac_f32_e32 v34, v33, v39
	s_waitcnt lgkmcnt(2)
	v_fmac_f32_e32 v34, v26, v50
	v_fmac_f32_e32 v34, v27, v51
	v_fmac_f32_e32 v34, v28, v52
	v_fmac_f32_e32 v34, v29, v53
	s_waitcnt lgkmcnt(1)
	v_fmac_f32_e32 v34, v22, v54
	v_fmac_f32_e32 v34, v23, v55
	v_fmac_f32_e32 v34, v24, v56
	v_fmac_f32_e32 v34, v25, v57
	s_waitcnt lgkmcnt(0)
	v_pk_mul_f32 v[36:37], v[0:1], v[58:59]
	ds_read_b128 v[50:53], v43 offset:256
	v_add_f32_e32 v34, v34, v36
	v_add_f32_e32 v34, v34, v37
	v_pk_mul_f32 v[36:37], v[2:3], v[60:61]
	s_nop 0
	v_add_f32_e32 v34, v34, v36
	v_add_f32_e32 v34, v34, v37
	v_min_f32_e32 v36, 0, v34
	v_mul_f32_e64 v34, |v34|, s35
	v_exp_f32_e32 v34, v34
	s_nop 0
	v_add_f32_e32 v34, 1.0, v34
	v_cmp_gt_f32_e32 vcc, s33, v34
	s_nop 1
	v_cndmask_b32_e64 v37, 0, 32, vcc
	v_ldexp_f32 v34, v34, v37
	v_log_f32_e32 v34, v34
	s_nop 0
	v_mul_f32_e32 v37, 0x3f317217, v34
	v_fma_f32 v37, v34, s36, -v37
	v_fmac_f32_e32 v37, 0x3377d1cf, v34
	v_fmac_f32_e32 v37, 0x3f317217, v34
	v_cmp_lt_f32_e64 s[12:13], |v34|, s37
	s_nop 1
	v_cndmask_b32_e64 v34, v34, v37, s[12:13]
	v_cndmask_b32_e32 v37, 0, v179, vcc
	v_sub_f32_e32 v34, v34, v37
	v_sub_f32_e32 v34, v36, v34
	ds_read_b128 v[36:39], v43 offset:64
	s_mov_b32 s12, 0x3d800000
	v_fma_f32 v34, v34, s12, 0
	s_waitcnt lgkmcnt(0)
	v_fma_f32 v40, v30, v36, v35
	v_fmac_f32_e32 v40, v31, v37
	v_fmac_f32_e32 v40, v32, v38
	v_fmac_f32_e32 v40, v33, v39
	ds_read_b128 v[36:39], v43 offset:80
	s_waitcnt lgkmcnt(0)
	v_fmac_f32_e32 v40, v26, v36
	v_fmac_f32_e32 v40, v27, v37
	v_fmac_f32_e32 v40, v28, v38
	v_fmac_f32_e32 v40, v29, v39
	ds_read_b128 v[36:39], v43 offset:96
	s_waitcnt lgkmcnt(0)
	v_fmac_f32_e32 v40, v22, v36
	v_fmac_f32_e32 v40, v23, v37
	v_fmac_f32_e32 v40, v24, v38
	v_fmac_f32_e32 v40, v25, v39
	ds_read_b128 v[36:39], v43 offset:112
	s_waitcnt lgkmcnt(0)
	v_pk_mul_f32 v[36:37], v[0:1], v[36:37]
	s_nop 0
	v_add_f32_e32 v36, v40, v36
	v_add_f32_e32 v40, v36, v37
	v_pk_mul_f32 v[36:37], v[2:3], v[38:39]
	s_nop 0
	v_add_f32_e32 v36, v40, v36
	v_add_f32_e32 v36, v36, v37
	v_min_f32_e32 v37, 0, v36
	v_mul_f32_e64 v36, |v36|, s35
	v_exp_f32_e32 v36, v36
	s_nop 0
	v_add_f32_e32 v36, 1.0, v36
	v_cmp_gt_f32_e32 vcc, s33, v36
	s_nop 1
	v_cndmask_b32_e64 v38, 0, 32, vcc
	v_ldexp_f32 v36, v36, v38
	v_log_f32_e32 v36, v36
	s_nop 0
	v_mul_f32_e32 v38, 0x3f317217, v36
	v_fma_f32 v38, v36, s36, -v38
	v_fmac_f32_e32 v38, 0x3377d1cf, v36
	v_fmac_f32_e32 v38, 0x3f317217, v36
	v_cmp_lt_f32_e64 s[12:13], |v36|, s37
	s_nop 1
	v_cndmask_b32_e64 v36, v36, v38, s[12:13]
	v_cndmask_b32_e32 v38, 0, v179, vcc
	v_sub_f32_e32 v36, v36, v38
	ds_read_b128 v[38:41], v43 offset:128
	v_sub_f32_e32 v36, v37, v36
	v_fmamk_f32 v36, v36, 0x3d800000, v34
	s_waitcnt lgkmcnt(0)
	v_fma_f32 v37, v30, v38, v35
	v_fmac_f32_e32 v37, v31, v39
	v_fmac_f32_e32 v37, v32, v40
	v_fmac_f32_e32 v37, v33, v41
	ds_read_b128 v[38:41], v43 offset:144
	s_waitcnt lgkmcnt(0)
	v_fmac_f32_e32 v37, v26, v38
	v_fmac_f32_e32 v37, v27, v39
	v_fmac_f32_e32 v37, v28, v40
	v_fmac_f32_e32 v37, v29, v41
	ds_read_b128 v[38:41], v43 offset:160
	s_waitcnt lgkmcnt(0)
	v_fmac_f32_e32 v37, v22, v38
	v_fmac_f32_e32 v37, v23, v39
	v_fmac_f32_e32 v37, v24, v40
	v_fmac_f32_e32 v37, v25, v41
	ds_read_b128 v[38:41], v43 offset:176
	s_waitcnt lgkmcnt(0)
	v_pk_mul_f32 v[38:39], v[0:1], v[38:39]
	s_nop 0
	v_add_f32_e32 v37, v37, v38
	v_add_f32_e32 v37, v37, v39
	v_pk_mul_f32 v[38:39], v[2:3], v[40:41]
	s_nop 0
	v_add_f32_e32 v37, v37, v38
	v_add_f32_e32 v37, v37, v39
	v_min_f32_e32 v38, 0, v37
	v_mul_f32_e64 v37, |v37|, s35
	v_exp_f32_e32 v37, v37
	s_nop 0
	v_add_f32_e32 v37, 1.0, v37
	v_cmp_gt_f32_e32 vcc, s33, v37
	s_nop 1
	v_cndmask_b32_e64 v39, 0, 32, vcc
	v_ldexp_f32 v37, v37, v39
	v_log_f32_e32 v37, v37
	s_nop 0
	v_mul_f32_e32 v39, 0x3f317217, v37
	v_fma_f32 v39, v37, s36, -v39
	v_fmac_f32_e32 v39, 0x3377d1cf, v37
	v_fmac_f32_e32 v39, 0x3f317217, v37
	v_cmp_lt_f32_e64 s[12:13], |v37|, s37
	s_nop 1
	v_cndmask_b32_e64 v37, v37, v39, s[12:13]
	v_cndmask_b32_e32 v39, 0, v179, vcc
	v_sub_f32_e32 v37, v37, v39
	v_sub_f32_e32 v37, v38, v37
	ds_read_b128 v[38:41], v43 offset:192
	v_fmamk_f32 v37, v37, 0x3d800000, v36
	s_waitcnt lgkmcnt(0)
	v_fma_f32 v49, v30, v38, v35
	v_fmac_f32_e32 v49, v31, v39
	v_fmac_f32_e32 v49, v32, v40
	v_fmac_f32_e32 v49, v33, v41
	ds_read_b128 v[38:41], v43 offset:208
	s_waitcnt lgkmcnt(0)
	v_fmac_f32_e32 v49, v26, v38
	v_fmac_f32_e32 v49, v27, v39
	v_fmac_f32_e32 v49, v28, v40
	v_fmac_f32_e32 v49, v29, v41
	ds_read_b128 v[38:41], v43 offset:224
	s_waitcnt lgkmcnt(0)
	v_fmac_f32_e32 v49, v22, v38
	v_fmac_f32_e32 v49, v23, v39
	v_fmac_f32_e32 v49, v24, v40
	v_fmac_f32_e32 v49, v25, v41
	ds_read_b128 v[38:41], v43 offset:240
	s_waitcnt lgkmcnt(0)
	v_pk_mul_f32 v[38:39], v[0:1], v[38:39]
	s_nop 0
	v_add_f32_e32 v38, v49, v38
	v_add_f32_e32 v49, v38, v39
	v_pk_mul_f32 v[38:39], v[2:3], v[40:41]
	s_nop 0
	v_add_f32_e32 v38, v49, v38
	v_add_f32_e32 v38, v38, v39
	v_min_f32_e32 v39, 0, v38
	v_mul_f32_e64 v38, |v38|, s35
	v_exp_f32_e32 v38, v38
	s_nop 0
	v_add_f32_e32 v38, 1.0, v38
	v_cmp_gt_f32_e32 vcc, s33, v38
	s_nop 1
	v_cndmask_b32_e64 v40, 0, 32, vcc
	v_ldexp_f32 v38, v38, v40
	v_log_f32_e32 v38, v38
	s_nop 0
	v_mul_f32_e32 v40, 0x3f317217, v38
	v_fma_f32 v40, v38, s36, -v40
	v_fmac_f32_e32 v40, 0x3377d1cf, v38
	v_fmac_f32_e32 v40, 0x3f317217, v38
	v_cmp_lt_f32_e64 s[12:13], |v38|, s37
	s_nop 1
	v_cndmask_b32_e64 v38, v38, v40, s[12:13]
	v_cndmask_b32_e32 v40, 0, v179, vcc
	v_sub_f32_e32 v38, v38, v40
	v_sub_f32_e32 v38, v39, v38
	v_fma_f32 v39, v30, v50, v35
	v_fmac_f32_e32 v39, v31, v51
	v_fmac_f32_e32 v39, v32, v52
	v_fmac_f32_e32 v39, v33, v53
	ds_read_b128 v[50:53], v43 offset:272
	v_fmamk_f32 v38, v38, 0x3d800000, v37
	s_waitcnt lgkmcnt(0)
	v_fmac_f32_e32 v39, v26, v50
	v_fmac_f32_e32 v39, v27, v51
	v_fmac_f32_e32 v39, v28, v52
	v_fmac_f32_e32 v39, v29, v53
	ds_read_b128 v[50:53], v43 offset:288
	s_waitcnt lgkmcnt(0)
	v_fmac_f32_e32 v39, v22, v50
	v_fmac_f32_e32 v39, v23, v51
	v_fmac_f32_e32 v39, v24, v52
	v_fmac_f32_e32 v39, v25, v53
	ds_read_b128 v[50:53], v43 offset:304
	s_waitcnt lgkmcnt(0)
	v_pk_mul_f32 v[40:41], v[0:1], v[50:51]
	s_nop 0
	v_add_f32_e32 v39, v39, v40
	v_add_f32_e32 v39, v39, v41
	v_pk_mul_f32 v[40:41], v[2:3], v[52:53]
	ds_read_b128 v[50:53], v43 offset:320
	v_add_f32_e32 v39, v39, v40
	v_add_f32_e32 v39, v39, v41
	v_min_f32_e32 v40, 0, v39
	v_mul_f32_e64 v39, |v39|, s35
	s_waitcnt lgkmcnt(0)
	v_fma_f32 v49, v30, v50, v35
	v_fmac_f32_e32 v49, v31, v51
	v_fmac_f32_e32 v49, v32, v52
	v_fmac_f32_e32 v49, v33, v53
	ds_read_b128 v[50:53], v43 offset:336
	v_exp_f32_e32 v39, v39
	s_waitcnt lgkmcnt(0)
	v_fmac_f32_e32 v49, v26, v50
	v_fmac_f32_e32 v49, v27, v51
	v_add_f32_e32 v39, 1.0, v39
	v_fmac_f32_e32 v49, v28, v52
	v_cmp_gt_f32_e32 vcc, s33, v39
	v_fmac_f32_e32 v49, v29, v53
	ds_read_b128 v[50:53], v43 offset:352
	v_cndmask_b32_e64 v41, 0, 32, vcc
	v_ldexp_f32 v39, v39, v41
	v_log_f32_e32 v39, v39
	s_waitcnt lgkmcnt(0)
	v_fmac_f32_e32 v49, v22, v50
	v_fmac_f32_e32 v49, v23, v51
	v_mul_f32_e32 v41, 0x3f317217, v39
	v_fmac_f32_e32 v49, v24, v52
	v_fma_f32 v41, v39, s36, -v41
	v_fmac_f32_e32 v49, v25, v53
	ds_read_b128 v[50:53], v43 offset:368
	v_fmac_f32_e32 v41, 0x3377d1cf, v39
	v_fmac_f32_e32 v41, 0x3f317217, v39
	v_cmp_lt_f32_e64 s[12:13], |v39|, s37
	s_nop 1
	v_cndmask_b32_e64 v39, v39, v41, s[12:13]
	v_cndmask_b32_e32 v41, 0, v179, vcc
	v_sub_f32_e32 v39, v39, v41
	v_sub_f32_e32 v39, v40, v39
	s_waitcnt lgkmcnt(0)
	v_pk_mul_f32 v[40:41], v[0:1], v[50:51]
	v_fmamk_f32 v39, v39, 0x3d800000, v38
	v_add_f32_e32 v40, v49, v40
	v_add_f32_e32 v49, v40, v41
	v_pk_mul_f32 v[40:41], v[2:3], v[52:53]
	ds_read_b128 v[50:53], v43 offset:384
	v_add_f32_e32 v40, v49, v40
	v_add_f32_e32 v40, v40, v41
	v_min_f32_e32 v41, 0, v40
	v_mul_f32_e64 v40, |v40|, s35
	v_exp_f32_e32 v40, v40
	s_nop 0
	v_add_f32_e32 v40, 1.0, v40
	v_cmp_gt_f32_e32 vcc, s33, v40
	s_nop 1
	v_cndmask_b32_e64 v49, 0, 32, vcc
	v_ldexp_f32 v40, v40, v49
	v_log_f32_e32 v40, v40
	s_nop 0
	v_mul_f32_e32 v49, 0x3f317217, v40
	v_fma_f32 v49, v40, s36, -v49
	v_fmac_f32_e32 v49, 0x3377d1cf, v40
	v_fmac_f32_e32 v49, 0x3f317217, v40
	v_cmp_lt_f32_e64 s[12:13], |v40|, s37
	s_nop 1
	v_cndmask_b32_e64 v40, v40, v49, s[12:13]
	v_cndmask_b32_e32 v49, 0, v179, vcc
	v_sub_f32_e32 v40, v40, v49
	v_sub_f32_e32 v40, v41, v40
	v_fmamk_f32 v41, v40, 0x3d800000, v39
	s_waitcnt lgkmcnt(0)
	v_fma_f32 v40, v30, v50, v35
	v_fmac_f32_e32 v40, v31, v51
	v_fmac_f32_e32 v40, v32, v52
	v_fmac_f32_e32 v40, v33, v53
	ds_read_b128 v[50:53], v43 offset:400
	s_waitcnt lgkmcnt(0)
	v_fmac_f32_e32 v40, v26, v50
	v_fmac_f32_e32 v40, v27, v51
	v_fmac_f32_e32 v40, v28, v52
	v_fmac_f32_e32 v40, v29, v53
	ds_read_b128 v[50:53], v43 offset:416
	s_waitcnt lgkmcnt(0)
	v_fmac_f32_e32 v40, v22, v50
	v_fmac_f32_e32 v40, v23, v51
	v_fmac_f32_e32 v40, v24, v52
	v_fmac_f32_e32 v40, v25, v53
	ds_read_b128 v[50:53], v43 offset:432
	s_waitcnt lgkmcnt(0)
	v_pk_mul_f32 v[50:51], v[0:1], v[50:51]
	s_nop 0
	v_add_f32_e32 v40, v40, v50
	v_add_f32_e32 v40, v40, v51
	v_pk_mul_f32 v[50:51], v[2:3], v[52:53]
	s_nop 0
	v_add_f32_e32 v40, v40, v50
	v_add_f32_e32 v40, v40, v51
	v_min_f32_e32 v49, 0, v40
	v_mul_f32_e64 v40, |v40|, s35
	v_exp_f32_e32 v40, v40
	s_nop 0
	v_add_f32_e32 v40, 1.0, v40
	v_cmp_gt_f32_e32 vcc, s33, v40
	s_nop 1
	v_cndmask_b32_e64 v50, 0, 32, vcc
	v_ldexp_f32 v40, v40, v50
	v_log_f32_e32 v40, v40
	s_nop 0
	v_mul_f32_e32 v50, 0x3f317217, v40
	v_fma_f32 v50, v40, s36, -v50
	v_fmac_f32_e32 v50, 0x3377d1cf, v40
	v_fmac_f32_e32 v50, 0x3f317217, v40
	v_cmp_lt_f32_e64 s[12:13], |v40|, s37
	s_nop 1
	v_cndmask_b32_e64 v40, v40, v50, s[12:13]
	v_cndmask_b32_e32 v50, 0, v179, vcc
	v_sub_f32_e32 v40, v40, v50
	ds_read_b128 v[50:53], v43 offset:448
	v_sub_f32_e32 v40, v49, v40
	v_fmamk_f32 v49, v40, 0x3d800000, v41
	s_waitcnt lgkmcnt(0)
	v_fma_f32 v40, v30, v50, v35
	v_fmac_f32_e32 v40, v31, v51
	v_fmac_f32_e32 v40, v32, v52
	v_fmac_f32_e32 v40, v33, v53
	ds_read_b128 v[50:53], v43 offset:464
	s_waitcnt lgkmcnt(0)
	v_fmac_f32_e32 v40, v26, v50
	v_fmac_f32_e32 v40, v27, v51
	v_fmac_f32_e32 v40, v28, v52
	v_fmac_f32_e32 v40, v29, v53
	ds_read_b128 v[50:53], v43 offset:480
	s_waitcnt lgkmcnt(0)
	v_fmac_f32_e32 v40, v22, v50
	v_fmac_f32_e32 v40, v23, v51
	v_fmac_f32_e32 v40, v24, v52
	v_fmac_f32_e32 v40, v25, v53
	ds_read_b128 v[50:53], v43 offset:496
	s_waitcnt lgkmcnt(0)
	v_pk_mul_f32 v[50:51], v[0:1], v[50:51]
	s_nop 0
	v_add_f32_e32 v40, v40, v50
	v_add_f32_e32 v40, v40, v51
	v_pk_mul_f32 v[50:51], v[2:3], v[52:53]
	ds_read_b128 v[52:55], v43 offset:512
	v_add_f32_e32 v40, v40, v50
	v_add_f32_e32 v40, v40, v51
	v_min_f32_e32 v50, 0, v40
	v_mul_f32_e64 v40, |v40|, s35
	v_exp_f32_e32 v40, v40
	s_nop 0
	v_add_f32_e32 v40, 1.0, v40
	v_cmp_gt_f32_e32 vcc, s33, v40
	s_nop 1
	v_cndmask_b32_e64 v51, 0, 32, vcc
	v_ldexp_f32 v40, v40, v51
	v_log_f32_e32 v40, v40
	s_nop 0
	v_mul_f32_e32 v51, 0x3f317217, v40
	v_fma_f32 v51, v40, s36, -v51
	v_fmac_f32_e32 v51, 0x3377d1cf, v40
	v_fmac_f32_e32 v51, 0x3f317217, v40
	v_cmp_lt_f32_e64 s[12:13], |v40|, s37
	s_nop 1
	v_cndmask_b32_e64 v40, v40, v51, s[12:13]
	v_cndmask_b32_e32 v51, 0, v179, vcc
	v_sub_f32_e32 v40, v40, v51
	v_sub_f32_e32 v40, v50, v40
	v_fmamk_f32 v51, v40, 0x3d800000, v49
	s_waitcnt lgkmcnt(0)
	v_fma_f32 v40, v30, v52, v35
	v_fmac_f32_e32 v40, v31, v53
	v_fmac_f32_e32 v40, v32, v54
	v_fmac_f32_e32 v40, v33, v55
	ds_read_b128 v[52:55], v43 offset:528
	s_waitcnt lgkmcnt(0)
	v_fmac_f32_e32 v40, v26, v52
	v_fmac_f32_e32 v40, v27, v53
	v_fmac_f32_e32 v40, v28, v54
	v_fmac_f32_e32 v40, v29, v55
	ds_read_b128 v[52:55], v43 offset:544
	s_waitcnt lgkmcnt(0)
	v_fmac_f32_e32 v40, v22, v52
	v_fmac_f32_e32 v40, v23, v53
	v_fmac_f32_e32 v40, v24, v54
	v_fmac_f32_e32 v40, v25, v55
	ds_read_b128 v[52:55], v43 offset:560
	s_waitcnt lgkmcnt(0)
	v_pk_mul_f32 v[52:53], v[0:1], v[52:53]
	s_nop 0
	v_add_f32_e32 v40, v40, v52
	v_add_f32_e32 v40, v40, v53
	v_pk_mul_f32 v[52:53], v[2:3], v[54:55]
	s_nop 0
	v_add_f32_e32 v40, v40, v52
	v_add_f32_e32 v40, v40, v53
	v_min_f32_e32 v50, 0, v40
	v_mul_f32_e64 v40, |v40|, s35
	v_exp_f32_e32 v40, v40
	s_nop 0
	v_add_f32_e32 v40, 1.0, v40
	v_cmp_gt_f32_e32 vcc, s33, v40
	s_nop 1
	v_cndmask_b32_e64 v52, 0, 32, vcc
	v_ldexp_f32 v40, v40, v52
	v_log_f32_e32 v40, v40
	s_nop 0
	v_mul_f32_e32 v52, 0x3f317217, v40
	v_fma_f32 v52, v40, s36, -v52
	v_fmac_f32_e32 v52, 0x3377d1cf, v40
	v_fmac_f32_e32 v52, 0x3f317217, v40
	v_cmp_lt_f32_e64 s[12:13], |v40|, s37
	s_nop 1
	v_cndmask_b32_e64 v40, v40, v52, s[12:13]
	v_cndmask_b32_e32 v52, 0, v179, vcc
	v_sub_f32_e32 v40, v40, v52
	ds_read_b128 v[52:55], v43 offset:576
	v_sub_f32_e32 v40, v50, v40
	v_fmamk_f32 v40, v40, 0x3d800000, v51
	s_waitcnt lgkmcnt(0)
	v_fma_f32 v50, v30, v52, v35
	v_fmac_f32_e32 v50, v31, v53
	v_fmac_f32_e32 v50, v32, v54
	v_fmac_f32_e32 v50, v33, v55
	ds_read_b128 v[52:55], v43 offset:592
	s_waitcnt lgkmcnt(0)
	v_fmac_f32_e32 v50, v26, v52
	v_fmac_f32_e32 v50, v27, v53
	v_fmac_f32_e32 v50, v28, v54
	v_fmac_f32_e32 v50, v29, v55
	ds_read_b128 v[52:55], v43 offset:608
	s_waitcnt lgkmcnt(0)
	v_fmac_f32_e32 v50, v22, v52
	v_fmac_f32_e32 v50, v23, v53
	v_fmac_f32_e32 v50, v24, v54
	v_fmac_f32_e32 v50, v25, v55
	ds_read_b128 v[52:55], v43 offset:624
	s_waitcnt lgkmcnt(0)
	v_pk_mul_f32 v[52:53], v[0:1], v[52:53]
	s_nop 0
	v_add_f32_e32 v50, v50, v52
	v_add_f32_e32 v50, v50, v53
	v_pk_mul_f32 v[52:53], v[2:3], v[54:55]
	s_nop 0
	v_add_f32_e32 v50, v50, v52
	v_add_f32_e32 v50, v50, v53
	v_min_f32_e32 v52, 0, v50
	v_mul_f32_e64 v50, |v50|, s35
	v_exp_f32_e32 v50, v50
	s_nop 0
	v_add_f32_e32 v50, 1.0, v50
	v_cmp_gt_f32_e32 vcc, s33, v50
	s_nop 1
	v_cndmask_b32_e64 v53, 0, 32, vcc
	v_ldexp_f32 v50, v50, v53
	v_log_f32_e32 v50, v50
	s_nop 0
	v_mul_f32_e32 v53, 0x3f317217, v50
	v_fma_f32 v53, v50, s36, -v53
	v_fmac_f32_e32 v53, 0x3377d1cf, v50
	v_fmac_f32_e32 v53, 0x3f317217, v50
	v_cmp_lt_f32_e64 s[12:13], |v50|, s37
	s_nop 1
	v_cndmask_b32_e64 v50, v50, v53, s[12:13]
	v_cndmask_b32_e32 v53, 0, v179, vcc
	v_sub_f32_e32 v50, v50, v53
	v_sub_f32_e32 v50, v52, v50
	ds_read_b128 v[52:55], v43 offset:640
	v_fmamk_f32 v50, v50, 0x3d800000, v40
	s_waitcnt lgkmcnt(0)
	v_fma_f32 v56, v30, v52, v35
	v_fmac_f32_e32 v56, v31, v53
	v_fmac_f32_e32 v56, v32, v54
	v_fmac_f32_e32 v56, v33, v55
	ds_read_b128 v[52:55], v43 offset:656
	s_waitcnt lgkmcnt(0)
	v_fmac_f32_e32 v56, v26, v52
	v_fmac_f32_e32 v56, v27, v53
	v_fmac_f32_e32 v56, v28, v54
	v_fmac_f32_e32 v56, v29, v55
	ds_read_b128 v[52:55], v43 offset:672
	s_waitcnt lgkmcnt(0)
	v_fmac_f32_e32 v56, v22, v52
	v_fmac_f32_e32 v56, v23, v53
	v_fmac_f32_e32 v56, v24, v54
	v_fmac_f32_e32 v56, v25, v55
	ds_read_b128 v[52:55], v43 offset:688
	s_waitcnt lgkmcnt(0)
	v_pk_mul_f32 v[52:53], v[0:1], v[52:53]
	s_nop 0
	v_add_f32_e32 v52, v56, v52
	v_add_f32_e32 v56, v52, v53
	v_pk_mul_f32 v[52:53], v[2:3], v[54:55]
	s_nop 0
	v_add_f32_e32 v52, v56, v52
	v_add_f32_e32 v52, v52, v53
	v_min_f32_e32 v53, 0, v52
	v_mul_f32_e64 v52, |v52|, s35
	v_exp_f32_e32 v52, v52
	s_nop 0
	v_add_f32_e32 v52, 1.0, v52
	v_cmp_gt_f32_e32 vcc, s33, v52
	s_nop 1
	v_cndmask_b32_e64 v54, 0, 32, vcc
	v_ldexp_f32 v52, v52, v54
	v_log_f32_e32 v52, v52
	s_nop 0
	v_mul_f32_e32 v54, 0x3f317217, v52
	v_fma_f32 v54, v52, s36, -v54
	v_fmac_f32_e32 v54, 0x3377d1cf, v52
	v_fmac_f32_e32 v54, 0x3f317217, v52
	v_cmp_lt_f32_e64 s[12:13], |v52|, s37
	s_nop 1
	v_cndmask_b32_e64 v52, v52, v54, s[12:13]
	v_cndmask_b32_e32 v54, 0, v179, vcc
	v_sub_f32_e32 v52, v52, v54
	ds_read_b128 v[54:57], v43 offset:704
	v_sub_f32_e32 v52, v53, v52
	v_fmamk_f32 v52, v52, 0x3d800000, v50
	s_waitcnt lgkmcnt(0)
	v_fma_f32 v53, v30, v54, v35
	v_fmac_f32_e32 v53, v31, v55
	v_fmac_f32_e32 v53, v32, v56
	v_fmac_f32_e32 v53, v33, v57
	ds_read_b128 v[54:57], v43 offset:720
	s_waitcnt lgkmcnt(0)
	v_fmac_f32_e32 v53, v26, v54
	v_fmac_f32_e32 v53, v27, v55
	v_fmac_f32_e32 v53, v28, v56
	v_fmac_f32_e32 v53, v29, v57
	ds_read_b128 v[54:57], v43 offset:736
	s_waitcnt lgkmcnt(0)
	v_fmac_f32_e32 v53, v22, v54
	v_fmac_f32_e32 v53, v23, v55
	v_fmac_f32_e32 v53, v24, v56
	v_fmac_f32_e32 v53, v25, v57
	ds_read_b128 v[54:57], v43 offset:752
	s_waitcnt lgkmcnt(0)
	v_pk_mul_f32 v[54:55], v[0:1], v[54:55]
	s_nop 0
	v_add_f32_e32 v53, v53, v54
	v_add_f32_e32 v53, v53, v55
	v_pk_mul_f32 v[54:55], v[2:3], v[56:57]
	s_nop 0
	v_add_f32_e32 v53, v53, v54
	v_add_f32_e32 v53, v53, v55
	v_min_f32_e32 v54, 0, v53
	v_mul_f32_e64 v53, |v53|, s35
	v_exp_f32_e32 v53, v53
	s_nop 0
	v_add_f32_e32 v53, 1.0, v53
	v_cmp_gt_f32_e32 vcc, s33, v53
	s_nop 1
	v_cndmask_b32_e64 v55, 0, 32, vcc
	v_ldexp_f32 v53, v53, v55
	v_log_f32_e32 v53, v53
	s_nop 0
	v_mul_f32_e32 v55, 0x3f317217, v53
	v_fma_f32 v55, v53, s36, -v55
	v_fmac_f32_e32 v55, 0x3377d1cf, v53
	v_fmac_f32_e32 v55, 0x3f317217, v53
	v_cmp_lt_f32_e64 s[12:13], |v53|, s37
	s_nop 1
	v_cndmask_b32_e64 v53, v53, v55, s[12:13]
	v_cndmask_b32_e32 v55, 0, v179, vcc
	v_sub_f32_e32 v53, v53, v55
	v_sub_f32_e32 v53, v54, v53
	ds_read_b128 v[54:57], v43 offset:768
	v_fmamk_f32 v53, v53, 0x3d800000, v52
	s_waitcnt lgkmcnt(0)
	v_fma_f32 v58, v30, v54, v35
	v_fmac_f32_e32 v58, v31, v55
	v_fmac_f32_e32 v58, v32, v56
	v_fmac_f32_e32 v58, v33, v57
	ds_read_b128 v[54:57], v43 offset:784
	s_waitcnt lgkmcnt(0)
	v_fmac_f32_e32 v58, v26, v54
	v_fmac_f32_e32 v58, v27, v55
	v_fmac_f32_e32 v58, v28, v56
	v_fmac_f32_e32 v58, v29, v57
	ds_read_b128 v[54:57], v43 offset:800
	s_waitcnt lgkmcnt(0)
	v_fmac_f32_e32 v58, v22, v54
	v_fmac_f32_e32 v58, v23, v55
	v_fmac_f32_e32 v58, v24, v56
	v_fmac_f32_e32 v58, v25, v57
	ds_read_b128 v[54:57], v43 offset:816
	s_waitcnt lgkmcnt(0)
	v_pk_mul_f32 v[54:55], v[0:1], v[54:55]
	s_nop 0
	v_add_f32_e32 v54, v58, v54
	v_add_f32_e32 v58, v54, v55
	v_pk_mul_f32 v[54:55], v[2:3], v[56:57]
	s_nop 0
	v_add_f32_e32 v54, v58, v54
	v_add_f32_e32 v54, v54, v55
	v_min_f32_e32 v55, 0, v54
	v_mul_f32_e64 v54, |v54|, s35
	v_exp_f32_e32 v54, v54
	s_nop 0
	v_add_f32_e32 v54, 1.0, v54
	v_cmp_gt_f32_e32 vcc, s33, v54
	s_nop 1
	v_cndmask_b32_e64 v56, 0, 32, vcc
	v_ldexp_f32 v54, v54, v56
	v_log_f32_e32 v54, v54
	s_nop 0
	v_mul_f32_e32 v56, 0x3f317217, v54
	v_fma_f32 v56, v54, s36, -v56
	v_fmac_f32_e32 v56, 0x3377d1cf, v54
	v_fmac_f32_e32 v56, 0x3f317217, v54
	v_cmp_lt_f32_e64 s[12:13], |v54|, s37
	s_nop 1
	v_cndmask_b32_e64 v54, v54, v56, s[12:13]
	v_cndmask_b32_e32 v56, 0, v179, vcc
	v_sub_f32_e32 v54, v54, v56
	ds_read_b128 v[56:59], v43 offset:832
	v_sub_f32_e32 v54, v55, v54
	v_fmamk_f32 v54, v54, 0x3d800000, v53
	s_waitcnt lgkmcnt(0)
	v_fma_f32 v55, v30, v56, v35
	v_fmac_f32_e32 v55, v31, v57
	v_fmac_f32_e32 v55, v32, v58
	v_fmac_f32_e32 v55, v33, v59
	ds_read_b128 v[56:59], v43 offset:848
	s_waitcnt lgkmcnt(0)
	v_fmac_f32_e32 v55, v26, v56
	v_fmac_f32_e32 v55, v27, v57
	v_fmac_f32_e32 v55, v28, v58
	v_fmac_f32_e32 v55, v29, v59
	ds_read_b128 v[56:59], v43 offset:864
	s_waitcnt lgkmcnt(0)
	v_fmac_f32_e32 v55, v22, v56
	v_fmac_f32_e32 v55, v23, v57
	v_pk_mul_f32 v[56:57], v[24:25], v[58:59]
	s_nop 0
	v_add_f32_e32 v55, v55, v56
	v_add_f32_e32 v55, v55, v57
	ds_read_b128 v[56:59], v43 offset:880
	s_waitcnt lgkmcnt(0)
	v_pk_mul_f32 v[56:57], v[0:1], v[56:57]
	s_nop 0
	v_add_f32_e32 v55, v55, v56
	v_add_f32_e32 v55, v55, v57
	v_pk_mul_f32 v[56:57], v[2:3], v[58:59]
	s_nop 0
	v_add_f32_e32 v55, v55, v56
	v_add_f32_e32 v55, v55, v57
	v_min_f32_e32 v56, 0, v55
	v_mul_f32_e64 v55, |v55|, s35
	v_exp_f32_e32 v55, v55
	s_nop 0
	v_add_f32_e32 v55, 1.0, v55
	v_cmp_gt_f32_e32 vcc, s33, v55
	s_nop 1
	v_cndmask_b32_e64 v57, 0, 32, vcc
	v_ldexp_f32 v55, v55, v57
	v_log_f32_e32 v55, v55
	s_nop 0
	v_mul_f32_e32 v57, 0x3f317217, v55
	v_fma_f32 v57, v55, s36, -v57
	v_fmac_f32_e32 v57, 0x3377d1cf, v55
	v_fmac_f32_e32 v57, 0x3f317217, v55
	v_cmp_lt_f32_e64 s[12:13], |v55|, s37
	s_nop 1
	v_cndmask_b32_e64 v55, v55, v57, s[12:13]
	v_cndmask_b32_e32 v57, 0, v179, vcc
	v_sub_f32_e32 v55, v55, v57
	v_sub_f32_e32 v55, v56, v55
	ds_read_b128 v[56:59], v43 offset:896
	v_fmamk_f32 v55, v55, 0x3d800000, v54
	s_waitcnt lgkmcnt(0)
	v_fma_f32 v60, v30, v56, v35
	v_fmac_f32_e32 v60, v31, v57
	v_fmac_f32_e32 v60, v32, v58
	v_fmac_f32_e32 v60, v33, v59
	ds_read_b128 v[56:59], v43 offset:912
	s_waitcnt lgkmcnt(0)
	v_fmac_f32_e32 v60, v26, v56
	v_fmac_f32_e32 v60, v27, v57
	v_fmac_f32_e32 v60, v28, v58
	v_fmac_f32_e32 v60, v29, v59
	ds_read_b128 v[56:59], v43 offset:928
	s_waitcnt lgkmcnt(0)
	v_fmac_f32_e32 v60, v22, v56
	v_fmac_f32_e32 v60, v23, v57
	v_pk_mul_f32 v[56:57], v[24:25], v[58:59]
	s_nop 0
	v_add_f32_e32 v56, v60, v56
	v_add_f32_e32 v60, v56, v57
	ds_read_b128 v[56:59], v43 offset:944
	s_waitcnt lgkmcnt(0)
	v_pk_mul_f32 v[56:57], v[0:1], v[56:57]
	s_nop 0
	v_add_f32_e32 v56, v60, v56
	v_add_f32_e32 v60, v56, v57
	v_pk_mul_f32 v[56:57], v[2:3], v[58:59]
	s_nop 0
	v_add_f32_e32 v56, v60, v56
	v_add_f32_e32 v56, v56, v57
	v_min_f32_e32 v57, 0, v56
	v_mul_f32_e64 v56, |v56|, s35
	v_exp_f32_e32 v56, v56
	s_nop 0
	v_add_f32_e32 v56, 1.0, v56
	v_cmp_gt_f32_e32 vcc, s33, v56
	s_nop 1
	v_cndmask_b32_e64 v58, 0, 32, vcc
	v_ldexp_f32 v56, v56, v58
	v_log_f32_e32 v56, v56
	s_nop 0
	v_mul_f32_e32 v58, 0x3f317217, v56
	v_fma_f32 v58, v56, s36, -v58
	v_fmac_f32_e32 v58, 0x3377d1cf, v56
	v_fmac_f32_e32 v58, 0x3f317217, v56
	v_cmp_lt_f32_e64 s[12:13], |v56|, s37
	s_nop 1
	v_cndmask_b32_e64 v56, v56, v58, s[12:13]
	v_cndmask_b32_e32 v58, 0, v179, vcc
	v_sub_f32_e32 v56, v56, v58
	ds_read_b128 v[58:61], v43 offset:960
	v_sub_f32_e32 v56, v57, v56
	v_fmamk_f32 v56, v56, 0x3d800000, v55
	s_waitcnt lgkmcnt(0)
	v_fmac_f32_e32 v35, v30, v58
	v_fmac_f32_e32 v35, v31, v59
	v_fmac_f32_e32 v35, v32, v60
	v_fmac_f32_e32 v35, v33, v61
	ds_read_b128 v[30:33], v43 offset:976
	s_waitcnt lgkmcnt(0)
	v_fmac_f32_e32 v35, v26, v30
	v_fmac_f32_e32 v35, v27, v31
	v_fmac_f32_e32 v35, v28, v32
	v_fmac_f32_e32 v35, v29, v33
	ds_read_b128 v[26:29], v43 offset:992
	s_waitcnt lgkmcnt(0)
	v_pk_mul_f32 v[22:23], v[22:23], v[26:27]
	s_nop 0
	v_add_f32_e32 v22, v35, v22
	v_add_f32_e32 v26, v22, v23
	v_pk_mul_f32 v[22:23], v[24:25], v[28:29]
	s_nop 0
	v_add_f32_e32 v22, v26, v22
	v_add_f32_e32 v26, v22, v23
	ds_read_b128 v[22:25], v43 offset:1008
	s_waitcnt lgkmcnt(0)
	v_pk_mul_f32 v[0:1], v[0:1], v[22:23]
	s_nop 0
	v_add_f32_e32 v0, v26, v0
	v_add_f32_e32 v22, v0, v1
	v_pk_mul_f32 v[0:1], v[2:3], v[24:25]
	s_nop 0
	v_add_f32_e32 v0, v22, v0
	v_add_f32_e32 v0, v0, v1
	v_min_f32_e32 v1, 0, v0
	v_mul_f32_e64 v0, |v0|, s35
	v_exp_f32_e32 v0, v0
	s_nop 0
	v_add_f32_e32 v0, 1.0, v0
	v_cmp_gt_f32_e32 vcc, s33, v0
	s_nop 1
	v_cndmask_b32_e64 v2, 0, 32, vcc
	v_ldexp_f32 v0, v0, v2
	v_log_f32_e32 v0, v0
	s_nop 0
	v_mul_f32_e32 v2, 0x3f317217, v0
	v_fma_f32 v2, v0, s36, -v2
	v_fmac_f32_e32 v2, 0x3377d1cf, v0
	v_fmac_f32_e32 v2, 0x3f317217, v0
	v_cmp_lt_f32_e64 s[12:13], |v0|, s37
	s_nop 1
	v_cndmask_b32_e64 v0, v0, v2, s[12:13]
	v_cndmask_b32_e32 v2, 0, v179, vcc
	v_sub_f32_e32 v0, v0, v2
	v_sub_f32_e32 v0, v1, v0
	v_fmamk_f32 v3, v0, 0x3d800000, v56
	ds_write_b32 v44, v3 offset:4096
	s_waitcnt lgkmcnt(0)
	s_barrier
	ds_read2st64_b32 v[0:1], v45 offset0:16 offset1:18
	ds_read2st64_b32 v[22:23], v45 offset0:20 offset1:22
	s_mov_b64 s[12:13], -1
	s_waitcnt lgkmcnt(1)
	v_add_f32_e32 v0, 0, v0
	v_cndmask_b32_e64 v2, 0, v0, s[4:5]
	v_add_f32_e32 v0, v0, v1
	v_add_f32_e32 v1, v1, v2
	v_cndmask_b32_e64 v1, v2, v1, s[6:7]
	s_waitcnt lgkmcnt(0)
	v_add_f32_e32 v2, v0, v22
	v_add_f32_e32 v0, v22, v1
	v_cndmask_b32_e64 v0, v1, v0, s[18:19]
	v_add_f32_e32 v1, v23, v0
	v_cndmask_b32_e64 v1, v0, v1, s[20:21]
	v_add_f32_e32 v24, v34, v1
	ds_read_u16 v0, v10 offset:8192
	v_mul_f32_e32 v22, 0x3fb8aa3b, v24
	v_exp_f32_e32 v22, v22
	s_waitcnt lgkmcnt(0)
	v_lshlrev_b32_e32 v0, 16, v0
	v_mul_f32_e32 v0, v22, v0
	v_cvt_pk_bf16_f32 v0, v0, s0
	ds_write_b16 v10, v0 offset:43008
	v_mul_f32_e32 v0, 0xbfb8aa3b, v24
	v_exp_f32_e32 v25, v0
	v_mov_b32_e32 v0, v23
	v_pk_add_f32 v[22:23], v[2:3], v[0:1]
	ds_read_u16 v3, v10 offset:8464
	v_sub_f32_e32 v0, v22, v24
	v_mul_f32_e32 v0, 0x3fb8aa3b, v0
	v_exp_f32_e32 v2, v0
	v_add_f32_e32 v0, v36, v1
	v_mul_f32_e32 v24, 0x3fb8aa3b, v0
	v_exp_f32_e32 v24, v24
	s_waitcnt lgkmcnt(0)
	v_lshlrev_b32_e32 v3, 16, v3
	v_mul_f32_e32 v3, v24, v3
	v_cvt_pk_bf16_f32 v3, v3, s0
	ds_write_b16 v10, v3 offset:43280
	v_mul_f32_e32 v3, 0xbfb8aa3b, v0
	v_sub_f32_e32 v0, v22, v0
	v_mul_f32_e32 v0, 0x3fb8aa3b, v0
	v_exp_f32_e32 v28, v3
	v_exp_f32_e32 v3, v0
	ds_read_u16 v0, v10 offset:25600
	ds_read_u16 v24, v10 offset:25872
	s_waitcnt lgkmcnt(1)
	v_lshlrev_b32_e32 v26, 16, v0
	v_mul_f32_e32 v0, v25, v26
	s_waitcnt lgkmcnt(0)
	v_lshlrev_b32_e32 v27, 16, v24
	v_cvt_pk_bf16_f32 v0, v0, s0
	ds_write_b16 v10, v0 offset:60416
	v_mul_f32_e32 v0, v28, v27
	v_cvt_pk_bf16_f32 v0, v0, s0
	v_pk_mul_f32 v[24:25], v[2:3], v[26:27]
	ds_write_b16 v10, v0 offset:60688
	v_add_f32_e32 v0, v37, v1
	ds_read_u16 v2, v10 offset:8736
	v_mul_f32_e32 v3, 0x3fb8aa3b, v0
	v_exp_f32_e32 v3, v3
	s_waitcnt lgkmcnt(0)
	v_lshlrev_b32_e32 v2, 16, v2
	v_mul_f32_e32 v2, v3, v2
	v_cvt_pk_bf16_f32 v2, v2, s0
	ds_write_b16 v10, v2 offset:43552
	v_mul_f32_e32 v2, 0xbfb8aa3b, v0
	v_sub_f32_e32 v0, v22, v0
	v_mul_f32_e32 v0, 0x3fb8aa3b, v0
	v_exp_f32_e32 v26, v2
	v_exp_f32_e32 v2, v0
	v_add_f32_e32 v0, v38, v1
	ds_read_u16 v3, v10 offset:9008
	v_mul_f32_e32 v27, 0x3fb8aa3b, v0
	v_exp_f32_e32 v27, v27
	s_waitcnt lgkmcnt(0)
	v_lshlrev_b32_e32 v3, 16, v3
	v_mul_f32_e32 v3, v27, v3
	ds_read_u16 v27, v10 offset:26144
	ds_read_u16 v28, v10 offset:26416
	v_cvt_pk_bf16_f32 v3, v3, s0
	ds_write_b16 v10, v3 offset:43824
	v_mul_f32_e32 v3, 0xbfb8aa3b, v0
	v_exp_f32_e32 v30, v3
	v_sub_f32_e32 v0, v22, v0
	v_mul_f32_e32 v0, 0x3fb8aa3b, v0
	s_waitcnt lgkmcnt(1)
	v_lshlrev_b32_e32 v29, 16, v28
	v_lshlrev_b32_e32 v28, 16, v27
	v_exp_f32_e32 v3, v0
	v_mul_f32_e32 v0, v26, v28
	v_cvt_pk_bf16_f32 v0, v0, s0
	ds_write_b16 v10, v0 offset:60960
	v_mul_f32_e32 v0, v30, v29
	v_cvt_pk_bf16_f32 v0, v0, s0
	v_pk_mul_f32 v[26:27], v[2:3], v[28:29]
	ds_write_b16 v10, v0 offset:61232
	v_add_f32_e32 v0, v39, v1
	ds_read_u16 v2, v10 offset:9280
	v_mul_f32_e32 v3, 0x3fb8aa3b, v0
	v_exp_f32_e32 v3, v3
	s_waitcnt lgkmcnt(0)
	v_lshlrev_b32_e32 v2, 16, v2
	v_mul_f32_e32 v2, v3, v2
	v_cvt_pk_bf16_f32 v2, v2, s0
	ds_write_b16 v10, v2 offset:44096
	v_mul_f32_e32 v2, 0xbfb8aa3b, v0
	v_sub_f32_e32 v0, v22, v0
	v_mul_f32_e32 v0, 0x3fb8aa3b, v0
	v_exp_f32_e32 v28, v2
	v_exp_f32_e32 v2, v0
	v_add_f32_e32 v0, v41, v1
	ds_read_u16 v3, v10 offset:9552
	v_mul_f32_e32 v29, 0x3fb8aa3b, v0
	v_exp_f32_e32 v29, v29
	s_waitcnt lgkmcnt(0)
	v_lshlrev_b32_e32 v3, 16, v3
	v_mul_f32_e32 v3, v29, v3
	v_cvt_pk_bf16_f32 v3, v3, s0
	ds_write_b16 v10, v3 offset:44368
	v_mul_f32_e32 v3, 0xbfb8aa3b, v0
	v_sub_f32_e32 v0, v22, v0
	v_mul_f32_e32 v0, 0x3fb8aa3b, v0
	v_exp_f32_e32 v32, v3
	v_exp_f32_e32 v3, v0
	ds_read_u16 v0, v10 offset:26688
	ds_read_u16 v29, v10 offset:26960
	s_waitcnt lgkmcnt(1)
	v_lshlrev_b32_e32 v30, 16, v0
	v_mul_f32_e32 v0, v28, v30
	s_waitcnt lgkmcnt(0)
	v_lshlrev_b32_e32 v31, 16, v29
	v_cvt_pk_bf16_f32 v0, v0, s0
	ds_write_b16 v10, v0 offset:61504
	v_mul_f32_e32 v0, v32, v31
	v_cvt_pk_bf16_f32 v0, v0, s0
	v_pk_mul_f32 v[28:29], v[2:3], v[30:31]
	ds_write_b16 v10, v0 offset:61776
	v_add_f32_e32 v0, v49, v1
	ds_read_u16 v2, v10 offset:9824
	v_mul_f32_e32 v3, 0x3fb8aa3b, v0
	v_exp_f32_e32 v3, v3
	s_waitcnt lgkmcnt(0)
	v_lshlrev_b32_e32 v2, 16, v2
	v_mul_f32_e32 v2, v3, v2
	v_cvt_pk_bf16_f32 v2, v2, s0
	ds_write_b16 v10, v2 offset:44640
	v_mul_f32_e32 v2, 0xbfb8aa3b, v0
	v_sub_f32_e32 v0, v22, v0
	v_mul_f32_e32 v0, 0x3fb8aa3b, v0
	v_exp_f32_e32 v30, v2
	v_exp_f32_e32 v2, v0
	v_add_f32_e32 v0, v51, v1
	ds_read_u16 v3, v10 offset:10096
	v_mul_f32_e32 v31, 0x3fb8aa3b, v0
	v_exp_f32_e32 v31, v31
	s_waitcnt lgkmcnt(0)
	v_lshlrev_b32_e32 v3, 16, v3
	v_mul_f32_e32 v3, v31, v3
	v_cvt_pk_bf16_f32 v3, v3, s0
	ds_write_b16 v10, v3 offset:44912
	v_mul_f32_e32 v3, 0xbfb8aa3b, v0
	v_sub_f32_e32 v0, v22, v0
	v_mul_f32_e32 v0, 0x3fb8aa3b, v0
	v_exp_f32_e32 v34, v3
	v_exp_f32_e32 v3, v0
	ds_read_u16 v0, v10 offset:27232
	ds_read_u16 v31, v10 offset:27504
	s_waitcnt lgkmcnt(1)
	v_lshlrev_b32_e32 v32, 16, v0
	v_mul_f32_e32 v0, v30, v32
	s_waitcnt lgkmcnt(0)
	v_lshlrev_b32_e32 v33, 16, v31
	v_cvt_pk_bf16_f32 v0, v0, s0
	ds_write_b16 v10, v0 offset:62048
	v_mul_f32_e32 v0, v34, v33
	v_cvt_pk_bf16_f32 v0, v0, s0
	v_pk_mul_f32 v[30:31], v[2:3], v[32:33]
	ds_write_b16 v10, v0 offset:62320
	v_add_f32_e32 v0, v40, v1
	ds_read_u16 v2, v10 offset:10368
	v_mul_f32_e32 v3, 0x3fb8aa3b, v0
	v_exp_f32_e32 v3, v3
	s_waitcnt lgkmcnt(0)
	v_lshlrev_b32_e32 v2, 16, v2
	v_mul_f32_e32 v2, v3, v2
	v_cvt_pk_bf16_f32 v2, v2, s0
	ds_write_b16 v10, v2 offset:45184
	v_mul_f32_e32 v2, 0xbfb8aa3b, v0
	v_sub_f32_e32 v0, v22, v0
	v_mul_f32_e32 v0, 0x3fb8aa3b, v0
	v_exp_f32_e32 v32, v2
	v_exp_f32_e32 v2, v0
	v_add_f32_e32 v0, v50, v1
	ds_read_u16 v3, v10 offset:10640
	v_mul_f32_e32 v33, 0x3fb8aa3b, v0
	v_exp_f32_e32 v33, v33
	s_waitcnt lgkmcnt(0)
	v_lshlrev_b32_e32 v3, 16, v3
	v_mul_f32_e32 v3, v33, v3
	v_cvt_pk_bf16_f32 v3, v3, s0
	ds_write_b16 v10, v3 offset:45456
	v_mul_f32_e32 v3, 0xbfb8aa3b, v0
	v_sub_f32_e32 v0, v22, v0
	v_mul_f32_e32 v0, 0x3fb8aa3b, v0
	v_exp_f32_e32 v36, v3
	v_exp_f32_e32 v3, v0
	ds_read_u16 v0, v10 offset:27776
	ds_read_u16 v33, v10 offset:28048
	s_waitcnt lgkmcnt(1)
	v_lshlrev_b32_e32 v34, 16, v0
	v_mul_f32_e32 v0, v32, v34
	s_waitcnt lgkmcnt(0)
	v_lshlrev_b32_e32 v35, 16, v33
	v_cvt_pk_bf16_f32 v0, v0, s0
	ds_write_b16 v10, v0 offset:62592
	v_mul_f32_e32 v0, v36, v35
	v_cvt_pk_bf16_f32 v0, v0, s0
	v_pk_mul_f32 v[32:33], v[2:3], v[34:35]
	ds_write_b16 v10, v0 offset:62864
	v_add_f32_e32 v0, v52, v1
	ds_read_u16 v2, v10 offset:10912
	v_mul_f32_e32 v3, 0x3fb8aa3b, v0
	v_exp_f32_e32 v3, v3
	s_waitcnt lgkmcnt(0)
	v_lshlrev_b32_e32 v2, 16, v2
	v_mul_f32_e32 v2, v3, v2
	v_cvt_pk_bf16_f32 v2, v2, s0
	ds_write_b16 v10, v2 offset:45728
	v_mul_f32_e32 v2, 0xbfb8aa3b, v0
	v_sub_f32_e32 v0, v22, v0
	v_mul_f32_e32 v0, 0x3fb8aa3b, v0
	v_exp_f32_e32 v34, v2
	v_exp_f32_e32 v2, v0
	v_add_f32_e32 v0, v53, v1
	ds_read_u16 v3, v10 offset:11184
	v_mul_f32_e32 v35, 0x3fb8aa3b, v0
	v_exp_f32_e32 v35, v35
	s_waitcnt lgkmcnt(0)
	v_lshlrev_b32_e32 v3, 16, v3
	v_mul_f32_e32 v3, v35, v3
	v_cvt_pk_bf16_f32 v3, v3, s0
	ds_write_b16 v10, v3 offset:46000
	v_mul_f32_e32 v3, 0xbfb8aa3b, v0
	v_sub_f32_e32 v0, v22, v0
	v_mul_f32_e32 v0, 0x3fb8aa3b, v0
	v_exp_f32_e32 v38, v3
	v_exp_f32_e32 v3, v0
	ds_read_u16 v0, v10 offset:28320
	ds_read_u16 v35, v10 offset:28592
	ds_read_u16 v39, v10 offset:29136
	s_waitcnt lgkmcnt(2)
	v_lshlrev_b32_e32 v36, 16, v0
	v_mul_f32_e32 v0, v34, v36
	s_waitcnt lgkmcnt(1)
	v_lshlrev_b32_e32 v37, 16, v35
	v_cvt_pk_bf16_f32 v0, v0, s0
	ds_write_b16 v10, v0 offset:63136
	v_mul_f32_e32 v0, v38, v37
	v_cvt_pk_bf16_f32 v0, v0, s0
	v_pk_mul_f32 v[34:35], v[2:3], v[36:37]
	ds_write_b16 v10, v0 offset:63408
	v_add_f32_e32 v0, v54, v1
	ds_read_u16 v2, v10 offset:11456
	ds_read_u16 v36, v10 offset:28864
	v_mul_f32_e32 v3, 0x3fb8aa3b, v0
	v_exp_f32_e32 v3, v3
	s_waitcnt lgkmcnt(4)
	v_lshlrev_b32_e32 v39, 16, v39
	s_waitcnt lgkmcnt(1)
	v_lshlrev_b32_e32 v2, 16, v2
	v_mul_f32_e32 v2, v3, v2
	v_cvt_pk_bf16_f32 v2, v2, s0
	ds_write_b16 v10, v2 offset:46272
	v_mul_f32_e32 v2, 0xbfb8aa3b, v0
	v_sub_f32_e32 v0, v22, v0
	v_mul_f32_e32 v0, 0x3fb8aa3b, v0
	v_exp_f32_e32 v37, v2
	v_exp_f32_e32 v2, v0
	v_add_f32_e32 v0, v55, v1
	ds_read_u16 v3, v10 offset:11728
	v_mul_f32_e32 v38, 0x3fb8aa3b, v0
	v_exp_f32_e32 v38, v38
	s_waitcnt lgkmcnt(0)
	v_lshlrev_b32_e32 v3, 16, v3
	v_mul_f32_e32 v3, v38, v3
	v_cvt_pk_bf16_f32 v3, v3, s0
	ds_write_b16 v10, v3 offset:46544
	v_mul_f32_e32 v3, 0xbfb8aa3b, v0
	v_exp_f32_e32 v40, v3
	v_sub_f32_e32 v0, v22, v0
	v_mul_f32_e32 v0, 0x3fb8aa3b, v0
	v_lshlrev_b32_e32 v38, 16, v36
	v_exp_f32_e32 v3, v0
	v_mul_f32_e32 v0, v37, v38
	v_cvt_pk_bf16_f32 v0, v0, s0
	ds_write_b16 v10, v0 offset:63680
	v_mul_f32_e32 v0, v40, v39
	v_cvt_pk_bf16_f32 v0, v0, s0
	ds_write_b16 v10, v0 offset:63952
	v_add_f32_e32 v0, v56, v1
	ds_read_u16 v1, v10 offset:12000
	v_pk_mul_f32 v[36:37], v[2:3], v[38:39]
	v_mul_f32_e32 v2, 0x3fb8aa3b, v0
	v_exp_f32_e32 v2, v2
	v_mul_f32_e32 v3, 0x3fb8aa3b, v23
	s_waitcnt lgkmcnt(0)
	v_lshlrev_b32_e32 v1, 16, v1
	v_exp_f32_e32 v3, v3
	v_mul_f32_e32 v1, v2, v1
	v_cvt_pk_bf16_f32 v1, v1, s0
	ds_write_b16 v10, v1 offset:46816
	v_mul_f32_e32 v1, 0xbfb8aa3b, v0
	ds_read_u16 v2, v10 offset:29408
	v_exp_f32_e32 v38, v1
	ds_read_u16 v1, v10 offset:12272
	v_sub_f32_e32 v0, v22, v0
	v_mul_f32_e32 v0, 0x3fb8aa3b, v0
	v_exp_f32_e32 v0, v0
	s_waitcnt lgkmcnt(1)
	v_lshlrev_b32_e32 v2, 16, v2
	s_waitcnt lgkmcnt(0)
	v_lshlrev_b32_e32 v1, 16, v1
	v_mul_f32_e32 v1, v3, v1
	v_cvt_pk_bf16_f32 v1, v1, s0
	ds_read_u16 v3, v10 offset:29680
	ds_write_b16 v10, v1 offset:47088
	v_mul_f32_e32 v1, 0xbfb8aa3b, v23
	v_exp_f32_e32 v39, v1
	v_sub_f32_e32 v1, v22, v23
	v_mul_f32_e32 v1, 0x3fb8aa3b, v1
	v_exp_f32_e32 v1, v1
	v_mul_f32_e32 v23, v38, v2
	s_waitcnt lgkmcnt(1)
	v_lshlrev_b32_e32 v3, 16, v3
	v_cvt_pk_bf16_f32 v23, v23, s0
	ds_write_b16 v10, v23 offset:64224
	v_mul_f32_e32 v23, v39, v3
	v_cvt_pk_bf16_f32 v23, v23, s0
	v_pk_mul_f32 v[38:39], v[0:1], v[2:3]
	ds_write_b16 v10, v23 offset:64496
	s_cbranch_scc0 .LBB0_333
	v_pk_mov_b32 v[0:1], v[38:39], v[38:39] op_sel:[1,0]
	v_pk_mov_b32 v[2:3], v[28:29], v[28:29] op_sel:[1,0]
	v_cvt_pk_bf16_f32 v50, v0, v1
	v_pk_mov_b32 v[0:1], v[36:37], v[36:37] op_sel:[1,0]
	v_pk_mov_b32 v[40:41], v[24:25], v[24:25] op_sel:[1,0]
	v_cvt_pk_bf16_f32 v51, v0, v1
	v_pk_mov_b32 v[0:1], v[34:35], v[34:35] op_sel:[1,0]
	s_mov_b64 s[12:13], 0
	v_cvt_pk_bf16_f32 v52, v0, v1
	v_pk_mov_b32 v[0:1], v[32:33], v[32:33] op_sel:[1,0]
	s_nop 0
	v_cvt_pk_bf16_f32 v53, v0, v1
	v_pk_mov_b32 v[0:1], v[30:31], v[30:31] op_sel:[1,0]
	s_nop 0
	v_cvt_pk_bf16_f32 v0, v0, v1
	v_cvt_pk_bf16_f32 v1, v2, v3
	v_pk_mov_b32 v[2:3], v[26:27], v[26:27] op_sel:[1,0]
	s_nop 0
	v_cvt_pk_bf16_f32 v2, v2, v3
	v_cvt_pk_bf16_f32 v3, v40, v41
	v_lshl_add_u64 v[40:41], v[14:15], 0, s[26:27]
	global_store_dwordx4 v[40:41], v[50:53], off

.LBB0_497:
	v_lshlrev_b64 v[148:149], 1, v[142:143]
	v_or_b32_e32 v148, 0x100, v148
	v_lshl_add_u64 v[148:149], s[26:27], 0, v[148:149]
	s_and_b64 vcc, exec, s[4:5]
	s_mov_b64 s[6:7], -1
	s_waitcnt vmcnt(15)
	v_lshlrev_b32_e32 v154, 16, v190
	v_and_b32_e32 v155, 0xffff0000, v190
	v_lshlrev_b32_e32 v156, 16, v191
	v_and_b32_e32 v157, 0xffff0000, v191
	v_lshlrev_b32_e32 v158, 16, v192
	v_and_b32_e32 v159, 0xffff0000, v192
	v_lshlrev_b32_e32 v162, 16, v193
	v_and_b32_e32 v163, 0xffff0000, v193
	v_pk_fma_f32 v[120:121], s[34:35], v[120:121], v[156:157]
	v_pk_fma_f32 v[118:119], s[20:21], v[118:119], v[154:155]
	v_pk_fma_f32 v[116:117], s[34:35], v[116:117], v[162:163]
	v_pk_fma_f32 v[114:115], s[20:21], v[114:115], v[158:159]
	s_cbranch_vccnz .LBB0_499
	s_mov_b64 s[6:7], 0
	global_store_dwordx4 v[146:147], v[118:121], off offset:512
	global_store_dwordx4 v[146:147], v[114:117], off offset:528

.LBB0_504:
	s_or_b64 exec, exec, s[14:15]
	v_or_b32_e32 v116, 16, v140
	s_waitcnt lgkmcnt(0)
	v_ashrrev_i32_e32 v117, 31, v116
	v_lshlrev_b64 v[116:117], 10, v[116:117]
	v_lshl_add_u64 v[118:119], v[116:117], 0, v[144:145]
	v_lshl_add_u64 v[120:121], v[118:119], 1, s[26:27]
	s_mov_b64 s[14:15], -1
	s_and_b64 vcc, exec, s[4:5]
	s_waitcnt vmcnt(15)
	v_lshlrev_b32_e32 v116, 16, v194
	v_and_b32_e32 v117, 0xffff0000, v194
	v_lshlrev_b32_e32 v124, 16, v195
	v_and_b32_e32 v125, 0xffff0000, v195
	v_lshlrev_b32_e32 v128, 16, v196
	v_and_b32_e32 v129, 0xffff0000, v196
	v_lshlrev_b32_e32 v126, 16, v197
	v_and_b32_e32 v127, 0xffff0000, v197
	v_pk_fma_f32 v[112:113], s[34:35], v[112:113], v[124:125]
	v_pk_fma_f32 v[110:111], s[20:21], v[110:111], v[116:117]
	v_pk_fma_f32 v[108:109], s[34:35], v[108:109], v[126:127]
	v_pk_fma_f32 v[106:107], s[20:21], v[106:107], v[128:129]
	v_lshl_add_u64 v[116:117], v[118:119], 2, s[22:23]
	s_cbranch_vccnz .LBB0_506
	s_mov_b64 s[14:15], 0
	global_store_dwordx4 v[116:117], v[110:113], off
	global_store_dwordx4 v[116:117], v[106:109], off offset:16

.LBB0_508:
	v_lshlrev_b64 v[118:119], 1, v[118:119]
	v_or_b32_e32 v118, 0x100, v118
	v_lshl_add_u64 v[118:119], s[26:27], 0, v[118:119]
	s_and_b64 vcc, exec, s[4:5]
	s_mov_b64 s[14:15], -1
	s_waitcnt vmcnt(15)
	v_lshlrev_b32_e32 v120, 16, v198
	v_and_b32_e32 v121, 0xffff0000, v198
	v_lshlrev_b32_e32 v124, 16, v199
	v_and_b32_e32 v125, 0xffff0000, v199
	v_lshlrev_b32_e32 v128, 16, v200
	v_and_b32_e32 v129, 0xffff0000, v200
	v_lshlrev_b32_e32 v126, 16, v201
	v_and_b32_e32 v127, 0xffff0000, v201
	v_pk_fma_f32 v[104:105], s[34:35], v[104:105], v[124:125]
	v_pk_fma_f32 v[102:103], s[20:21], v[102:103], v[120:121]
	v_pk_fma_f32 v[100:101], s[34:35], v[100:101], v[126:127]
	v_pk_fma_f32 v[98:99], s[20:21], v[98:99], v[128:129]
	s_cbranch_vccnz .LBB0_510
	s_mov_b64 s[14:15], 0
	global_store_dwordx4 v[116:117], v[102:105], off offset:512
	global_store_dwordx4 v[116:117], v[98:101], off offset:528

.LBB0_515:
	s_or_b64 exec, exec, s[14:15]
	v_or_b32_e32 v98, 32, v140
	s_waitcnt lgkmcnt(0)
	v_ashrrev_i32_e32 v99, 31, v98
	v_lshlrev_b64 v[98:99], 10, v[98:99]
	v_lshl_add_u64 v[100:101], v[98:99], 0, v[144:145]
	v_lshl_add_u64 v[102:103], v[100:101], 1, s[26:27]
	s_mov_b64 s[14:15], -1
	s_and_b64 vcc, exec, s[4:5]
	s_waitcnt vmcnt(15)
	v_lshlrev_b32_e32 v98, 16, v202
	v_and_b32_e32 v99, 0xffff0000, v202
	v_lshlrev_b32_e32 v104, 16, v203
	v_and_b32_e32 v105, 0xffff0000, v203
	v_lshlrev_b32_e32 v108, 16, v204
	v_and_b32_e32 v109, 0xffff0000, v204
	v_lshlrev_b32_e32 v106, 16, v205
	v_and_b32_e32 v107, 0xffff0000, v205
	v_pk_fma_f32 v[94:95], s[34:35], v[94:95], v[104:105]
	v_pk_fma_f32 v[92:93], s[20:21], v[92:93], v[98:99]
	v_pk_fma_f32 v[90:91], s[34:35], v[90:91], v[106:107]
	v_pk_fma_f32 v[88:89], s[20:21], v[88:89], v[108:109]
	v_lshl_add_u64 v[98:99], v[100:101], 2, s[22:23]
	s_cbranch_vccnz .LBB0_517
	s_mov_b64 s[14:15], 0
	global_store_dwordx4 v[98:99], v[92:95], off
	global_store_dwordx4 v[98:99], v[88:91], off offset:16

.LBB0_519:
	v_lshlrev_b64 v[100:101], 1, v[100:101]
	v_or_b32_e32 v100, 0x100, v100
	v_lshl_add_u64 v[100:101], s[26:27], 0, v[100:101]
	s_and_b64 vcc, exec, s[4:5]
	s_mov_b64 s[14:15], -1
	s_waitcnt vmcnt(15)
	v_lshlrev_b32_e32 v106, 16, v206
	v_and_b32_e32 v107, 0xffff0000, v206
	v_lshlrev_b32_e32 v102, 16, v207
	v_and_b32_e32 v103, 0xffff0000, v207
	v_lshlrev_b32_e32 v108, 16, v208
	v_and_b32_e32 v109, 0xffff0000, v208
	v_lshlrev_b32_e32 v104, 16, v209
	v_and_b32_e32 v105, 0xffff0000, v209
	v_pk_fma_f32 v[86:87], s[34:35], v[86:87], v[102:103]
	v_pk_fma_f32 v[84:85], s[20:21], v[84:85], v[106:107]
	v_pk_fma_f32 v[82:83], s[34:35], v[82:83], v[104:105]
	v_pk_fma_f32 v[80:81], s[20:21], v[80:81], v[108:109]
	s_cbranch_vccnz .LBB0_521
	s_mov_b64 s[14:15], 0
	global_store_dwordx4 v[98:99], v[84:87], off offset:512
	global_store_dwordx4 v[98:99], v[80:83], off offset:528

.LBB0_526:
	s_or_b64 exec, exec, s[14:15]
	v_or_b32_e32 v80, 48, v140
	s_waitcnt lgkmcnt(0)
	v_ashrrev_i32_e32 v81, 31, v80
	v_lshlrev_b64 v[80:81], 10, v[80:81]
	v_lshl_add_u64 v[82:83], v[80:81], 0, v[144:145]
	v_lshl_add_u64 v[84:85], v[82:83], 1, s[26:27]
	s_mov_b64 s[14:15], -1
	s_and_b64 vcc, exec, s[4:5]
	s_waitcnt vmcnt(15)
	v_lshlrev_b32_e32 v80, 16, v210
	v_and_b32_e32 v81, 0xffff0000, v210
	v_lshlrev_b32_e32 v86, 16, v211
	v_and_b32_e32 v87, 0xffff0000, v211
	v_lshlrev_b32_e32 v90, 16, v212
	v_and_b32_e32 v91, 0xffff0000, v212
	v_lshlrev_b32_e32 v88, 16, v213
	v_and_b32_e32 v89, 0xffff0000, v213
	v_pk_fma_f32 v[78:79], s[34:35], v[78:79], v[86:87]
	v_pk_fma_f32 v[76:77], s[20:21], v[76:77], v[80:81]
	v_pk_fma_f32 v[74:75], s[34:35], v[74:75], v[88:89]
	v_pk_fma_f32 v[72:73], s[20:21], v[72:73], v[90:91]
	v_lshl_add_u64 v[80:81], v[82:83], 2, s[22:23]
	s_cbranch_vccnz .LBB0_528
	s_mov_b64 s[14:15], 0
	global_store_dwordx4 v[80:81], v[76:79], off
	global_store_dwordx4 v[80:81], v[72:75], off offset:16

.LBB0_530:
	v_lshlrev_b64 v[82:83], 1, v[82:83]
	v_or_b32_e32 v82, 0x100, v82
	v_lshl_add_u64 v[82:83], s[26:27], 0, v[82:83]
	s_and_b64 vcc, exec, s[4:5]
	s_mov_b64 s[14:15], -1
	s_waitcnt vmcnt(15)
	v_lshlrev_b32_e32 v88, 16, v214
	v_and_b32_e32 v89, 0xffff0000, v214
	v_lshlrev_b32_e32 v84, 16, v215
	v_and_b32_e32 v85, 0xffff0000, v215
	v_lshlrev_b32_e32 v90, 16, v216
	v_and_b32_e32 v91, 0xffff0000, v216
	v_lshlrev_b32_e32 v86, 16, v217
	v_and_b32_e32 v87, 0xffff0000, v217
	v_pk_fma_f32 v[70:71], s[34:35], v[70:71], v[84:85]
	v_pk_fma_f32 v[68:69], s[20:21], v[68:69], v[88:89]
	v_pk_fma_f32 v[66:67], s[34:35], v[66:67], v[86:87]
	v_pk_fma_f32 v[64:65], s[20:21], v[64:65], v[90:91]
	s_cbranch_vccnz .LBB0_532
	s_mov_b64 s[14:15], 0
	global_store_dwordx4 v[80:81], v[68:71], off offset:512
	global_store_dwordx4 v[80:81], v[64:67], off offset:528

.LBB0_537:
	s_or_b64 exec, exec, s[14:15]
	s_mov_b64 s[14:15], 0x20000
	v_lshl_add_u64 v[66:67], v[142:143], 0, s[14:15]
	v_lshl_add_u64 v[68:69], v[66:67], 1, s[26:27]
	s_mov_b64 s[14:15], -1
	s_and_b64 vcc, exec, s[4:5]
	s_waitcnt vmcnt(15)
	v_lshlrev_b32_e32 v64, 16, v218
	s_waitcnt lgkmcnt(0)
	v_and_b32_e32 v65, 0xffff0000, v218
	v_lshlrev_b32_e32 v70, 16, v219
	v_and_b32_e32 v71, 0xffff0000, v219
	v_lshlrev_b32_e32 v74, 16, v220
	v_and_b32_e32 v75, 0xffff0000, v220
	v_lshlrev_b32_e32 v72, 16, v221
	v_and_b32_e32 v73, 0xffff0000, v221
	v_pk_fma_f32 v[62:63], s[34:35], v[62:63], v[70:71]
	v_pk_fma_f32 v[60:61], s[20:21], v[60:61], v[64:65]
	v_pk_fma_f32 v[58:59], s[34:35], v[58:59], v[72:73]
	v_pk_fma_f32 v[56:57], s[20:21], v[56:57], v[74:75]
	v_lshl_add_u64 v[64:65], v[66:67], 2, s[22:23]
	s_cbranch_vccnz .LBB0_539
	s_mov_b64 s[14:15], 0
	global_store_dwordx4 v[64:65], v[60:63], off
	global_store_dwordx4 v[64:65], v[56:59], off offset:16

.LBB0_541:
	v_lshlrev_b64 v[66:67], 1, v[66:67]
	v_or_b32_e32 v66, 0x100, v66
	v_lshl_add_u64 v[66:67], s[26:27], 0, v[66:67]
	s_and_b64 vcc, exec, s[4:5]
	s_mov_b64 s[14:15], -1
	s_waitcnt vmcnt(15)
	v_lshlrev_b32_e32 v72, 16, v222
	v_and_b32_e32 v73, 0xffff0000, v222
	v_lshlrev_b32_e32 v68, 16, v223
	v_and_b32_e32 v69, 0xffff0000, v223
	v_lshlrev_b32_e32 v74, 16, v224
	v_and_b32_e32 v75, 0xffff0000, v224
	v_lshlrev_b32_e32 v70, 16, v225
	v_and_b32_e32 v71, 0xffff0000, v225
	v_pk_fma_f32 v[54:55], s[34:35], v[54:55], v[68:69]
	v_pk_fma_f32 v[52:53], s[20:21], v[52:53], v[72:73]
	v_pk_fma_f32 v[50:51], s[34:35], v[50:51], v[70:71]
	v_pk_fma_f32 v[48:49], s[20:21], v[48:49], v[74:75]
	s_cbranch_vccnz .LBB0_543
	s_mov_b64 s[14:15], 0
	global_store_dwordx4 v[64:65], v[52:55], off offset:512
	global_store_dwordx4 v[64:65], v[48:51], off offset:528

.LBB0_548:
	s_or_b64 exec, exec, s[14:15]
	s_mov_b64 s[14:15], 0x24000
	v_lshl_add_u64 v[50:51], v[142:143], 0, s[14:15]
	v_lshl_add_u64 v[52:53], v[50:51], 1, s[26:27]
	s_mov_b64 s[14:15], -1
	s_and_b64 vcc, exec, s[4:5]
	s_waitcnt vmcnt(15)
	v_lshlrev_b32_e32 v48, 16, v226
	s_waitcnt lgkmcnt(0)
	v_and_b32_e32 v49, 0xffff0000, v226
	v_lshlrev_b32_e32 v54, 16, v227
	v_and_b32_e32 v55, 0xffff0000, v227
	v_lshlrev_b32_e32 v58, 16, v228
	v_and_b32_e32 v59, 0xffff0000, v228
	v_lshlrev_b32_e32 v56, 16, v229
	v_and_b32_e32 v57, 0xffff0000, v229
	v_pk_fma_f32 v[46:47], s[34:35], v[46:47], v[54:55]
	v_pk_fma_f32 v[44:45], s[20:21], v[44:45], v[48:49]
	v_pk_fma_f32 v[42:43], s[34:35], v[42:43], v[56:57]
	v_pk_fma_f32 v[40:41], s[20:21], v[40:41], v[58:59]
	v_lshl_add_u64 v[48:49], v[50:51], 2, s[22:23]
	s_cbranch_vccnz .LBB0_550
	s_mov_b64 s[14:15], 0
	global_store_dwordx4 v[48:49], v[44:47], off
	global_store_dwordx4 v[48:49], v[40:43], off offset:16

.LBB0_552:
	v_lshlrev_b64 v[50:51], 1, v[50:51]
	v_or_b32_e32 v50, 0x100, v50
	v_lshl_add_u64 v[50:51], s[26:27], 0, v[50:51]
	s_and_b64 vcc, exec, s[4:5]
	s_mov_b64 s[14:15], -1
	s_waitcnt vmcnt(15)
	v_lshlrev_b32_e32 v56, 16, v166
	v_and_b32_e32 v57, 0xffff0000, v166
	v_lshlrev_b32_e32 v52, 16, v167
	v_and_b32_e32 v53, 0xffff0000, v167
	v_lshlrev_b32_e32 v58, 16, v168
	v_and_b32_e32 v59, 0xffff0000, v168
	v_lshlrev_b32_e32 v54, 16, v169
	v_and_b32_e32 v55, 0xffff0000, v169
	v_pk_fma_f32 v[38:39], s[34:35], v[38:39], v[52:53]
	v_pk_fma_f32 v[36:37], s[20:21], v[36:37], v[56:57]
	v_pk_fma_f32 v[34:35], s[34:35], v[34:35], v[54:55]
	v_pk_fma_f32 v[32:33], s[20:21], v[32:33], v[58:59]
	s_cbranch_vccnz .LBB0_554
	s_mov_b64 s[14:15], 0
	global_store_dwordx4 v[48:49], v[36:39], off offset:512
	global_store_dwordx4 v[48:49], v[32:35], off offset:528

.LBB0_559:
	s_or_b64 exec, exec, s[14:15]
	s_mov_b64 s[14:15], 0x28000
	v_lshl_add_u64 v[34:35], v[142:143], 0, s[14:15]
	v_lshl_add_u64 v[36:37], v[34:35], 1, s[26:27]
	s_mov_b64 s[14:15], -1
	s_and_b64 vcc, exec, s[4:5]
	s_waitcnt vmcnt(15)
	v_lshlrev_b32_e32 v32, 16, v170
	s_waitcnt lgkmcnt(0)
	v_and_b32_e32 v33, 0xffff0000, v170
	v_lshlrev_b32_e32 v38, 16, v171
	v_and_b32_e32 v39, 0xffff0000, v171
	v_lshlrev_b32_e32 v42, 16, v172
	v_and_b32_e32 v43, 0xffff0000, v172
	v_lshlrev_b32_e32 v40, 16, v173
	v_and_b32_e32 v41, 0xffff0000, v173
	v_pk_fma_f32 v[30:31], s[34:35], v[30:31], v[38:39]
	v_pk_fma_f32 v[28:29], s[20:21], v[28:29], v[32:33]
	v_pk_fma_f32 v[26:27], s[34:35], v[26:27], v[40:41]
	v_pk_fma_f32 v[24:25], s[20:21], v[24:25], v[42:43]
	v_lshl_add_u64 v[32:33], v[34:35], 2, s[22:23]
	s_cbranch_vccnz .LBB0_561
	s_mov_b64 s[14:15], 0
	global_store_dwordx4 v[32:33], v[28:31], off
	global_store_dwordx4 v[32:33], v[24:27], off offset:16

.LBB0_563:
	v_lshlrev_b64 v[34:35], 1, v[34:35]
	v_or_b32_e32 v34, 0x100, v34
	v_lshl_add_u64 v[34:35], s[26:27], 0, v[34:35]
	s_and_b64 vcc, exec, s[4:5]
	s_mov_b64 s[14:15], -1
	s_waitcnt vmcnt(15)
	v_lshlrev_b32_e32 v40, 16, v232
	v_and_b32_e32 v41, 0xffff0000, v232
	v_lshlrev_b32_e32 v36, 16, v233
	v_and_b32_e32 v37, 0xffff0000, v233
	v_lshlrev_b32_e32 v42, 16, v234
	v_and_b32_e32 v43, 0xffff0000, v234
	v_lshlrev_b32_e32 v38, 16, v235
	v_and_b32_e32 v39, 0xffff0000, v235
	v_pk_fma_f32 v[22:23], s[34:35], v[22:23], v[36:37]
	v_pk_fma_f32 v[20:21], s[20:21], v[20:21], v[40:41]
	v_pk_fma_f32 v[18:19], s[34:35], v[18:19], v[38:39]
	v_pk_fma_f32 v[16:17], s[20:21], v[16:17], v[42:43]
	s_cbranch_vccnz .LBB0_565
	s_mov_b64 s[14:15], 0
	global_store_dwordx4 v[32:33], v[20:23], off offset:512
	global_store_dwordx4 v[32:33], v[16:19], off offset:528

.LBB0_570:
	s_or_b64 exec, exec, s[14:15]
	s_mov_b64 s[14:15], 0x2c000
	v_lshl_add_u64 v[18:19], v[142:143], 0, s[14:15]
	v_lshl_add_u64 v[20:21], v[18:19], 1, s[26:27]
	s_mov_b64 s[14:15], -1
	s_and_b64 vcc, exec, s[4:5]
	s_waitcnt vmcnt(15)
	v_lshlrev_b32_e32 v16, 16, v242
	s_waitcnt lgkmcnt(0)
	v_and_b32_e32 v17, 0xffff0000, v242
	v_lshlrev_b32_e32 v22, 16, v243
	v_and_b32_e32 v23, 0xffff0000, v243
	v_lshlrev_b32_e32 v26, 16, v244
	v_and_b32_e32 v27, 0xffff0000, v244
	v_lshlrev_b32_e32 v24, 16, v245
	v_and_b32_e32 v25, 0xffff0000, v245
	v_pk_fma_f32 v[14:15], s[34:35], v[14:15], v[22:23]
	v_pk_fma_f32 v[12:13], s[20:21], v[12:13], v[16:17]
	v_pk_fma_f32 v[10:11], s[34:35], v[10:11], v[24:25]
	v_pk_fma_f32 v[8:9], s[20:21], v[8:9], v[26:27]
	v_lshl_add_u64 v[16:17], v[18:19], 2, s[22:23]
	s_cbranch_vccnz .LBB0_572
	s_mov_b64 s[14:15], 0
	global_store_dwordx4 v[16:17], v[12:15], off
	global_store_dwordx4 v[16:17], v[8:11], off offset:16

.LBB0_574:
	v_lshlrev_b64 v[18:19], 1, v[18:19]
	v_or_b32_e32 v18, 0x100, v18
	v_lshl_add_u64 v[18:19], s[26:27], 0, v[18:19]
	s_and_b64 vcc, exec, s[4:5]
	s_mov_b64 s[4:5], -1
	s_waitcnt vmcnt(15)
	v_lshlrev_b32_e32 v24, 16, v246
	v_and_b32_e32 v25, 0xffff0000, v246
	v_lshlrev_b32_e32 v20, 16, v247
	v_and_b32_e32 v21, 0xffff0000, v247
	v_lshlrev_b32_e32 v26, 16, v248
	v_and_b32_e32 v27, 0xffff0000, v248
	v_lshlrev_b32_e32 v22, 16, v249
	v_and_b32_e32 v23, 0xffff0000, v249
	v_pk_fma_f32 v[6:7], s[34:35], v[6:7], v[20:21]
	v_pk_fma_f32 v[4:5], s[20:21], v[4:5], v[24:25]
	v_pk_fma_f32 v[2:3], s[34:35], v[2:3], v[22:23]
	v_pk_fma_f32 v[0:1], s[20:21], v[0:1], v[26:27]
	s_cbranch_vccnz .LBB0_576
	s_mov_b64 s[4:5], 0
	global_store_dwordx4 v[16:17], v[4:7], off offset:512
	global_store_dwordx4 v[16:17], v[0:3], off offset:528
